# v75 + stage waits removed + both sparse tile-top waits counted + per-phase setprio in the sparse loop + K/V load 0.75 tile in the split + RNN/sparse start loads batched + G1 skew s_sleep 40
# speedup vs baseline: 1.0106x; 1.0041x over previous
.Lspb_wd:
	s_mov_b32 s98, 0
	ds_write_b128 v201, v[92:95]
	ds_write_b128 v201, v[108:111] offset:1280
	ds_read_b128 v[112:115], v202
	ds_read_b128 v[116:119], v202 offset:32
	ds_write_b128 v201, v[104:107]
	ds_write_b128 v201, v[88:91] offset:1280
	ds_read_b128 v[120:123], v202
	ds_read_b128 v[124:127], v202 offset:32
	ds_write_b128 v201, v[84:87]
	ds_write_b128 v201, v[100:103] offset:1280
	ds_read_b128 v[128:131], v202
	ds_read_b128 v[132:135], v202 offset:32
	ds_write_b128 v201, v[96:99]
	ds_write_b128 v201, v[80:83] offset:1280
	ds_read_b128 v[136:139], v202
	ds_read_b128 v[140:143], v202 offset:32
	s_add_i32 s67, s66, 1
	v_cmp_ge_u32_e64 s[6:7], s67, v186
	s_and_b64 vcc, exec, s[6:7]
	s_cbranch_vccnz .LBB0_833
	ds_bpermute_b32 v0, v188, v206
	ds_bpermute_b32 v4, v189, v206
	s_ashr_i32 s8, s38, 8
	s_ashr_i32 s9, s8, 31
	s_lshl_b64 s[8:9], s[8:9], 13
	s_waitcnt lgkmcnt(1)
	v_lshrrev_b32_e32 v1, 2, v0
	v_cmp_ne_u32_e32 vcc, -1, v0
	s_waitcnt lgkmcnt(0)
	v_lshrrev_b32_e32 v5, 2, v4
	s_lshl_b32 s12, s38, 3
	v_cndmask_b32_e32 v176, 0, v1, vcc
	v_cmp_ne_u32_e32 vcc, -1, v4
	v_lshl_add_u64 v[0:1], s[8:9], 0, v[176:177]
	v_lshlrev_b64 v[0:1], 11, v[0:1]
	v_cndmask_b32_e32 v176, 0, v5, vcc
	v_lshl_add_u64 v[4:5], s[8:9], 0, v[176:177]
	v_lshl_add_u64 v[0:1], s[34:35], 0, v[0:1]
	s_and_b32 s12, s12, 0x700
	v_lshlrev_b64 v[4:5], 11, v[4:5]
	v_lshl_add_u64 v[0:1], v[0:1], 0, s[12:13]
	v_mov_b32_e32 v185, v177
	v_lshl_add_u64 v[4:5], s[34:35], 0, v[4:5]
	v_lshl_add_u64 v[0:1], v[0:1], 0, v[184:185]
	v_lshl_add_u64 v[4:5], v[4:5], 0, s[12:13]
	v_lshl_add_u64 v[4:5], v[4:5], 0, v[184:185]
	global_load_dwordx4 v[92:95], v[0:1], off
	global_load_dwordx4 v[104:107], v[0:1], off offset:64
	global_load_dwordx4 v[108:111], v[4:5], off
	global_load_dwordx4 v[88:91], v[4:5], off offset:64
	global_load_dwordx4 v[84:87], v[0:1], off offset:128
	global_load_dwordx4 v[96:99], v[0:1], off offset:192
	global_load_dwordx4 v[100:103], v[4:5], off offset:128
	global_load_dwordx4 v[80:83], v[4:5], off offset:192
